# GEMM k-loops of Ph4/Ph5/Ph6: the 12 global loads of the even step are spread over all 16 MFMAs (three loads, one gap) instead of the first 12
# speedup vs baseline: 1.0100x; 1.0100x over previous
.Lg4_noraise:
.Lg4_loop:
	v_add_u32_e32 v190, s40, v186
	v_add_u32_e32 v191, s40, v187
	v_add_u32_e32 v250, s40, v188
	v_add_u32_e32 v251, s40, v189
	ds_read_b128 v[200:203], v190
	ds_read_b128 v[204:207], v190 offset:2048
	ds_read_b128 v[222:225], v250
	ds_read_b128 v[226:229], v250 offset:2048
	ds_read_b128 v[230:233], v250 offset:4096
	ds_read_b128 v[234:237], v250 offset:6144
	s_waitcnt lgkmcnt(3)
	v_mfma_f32_32x32x16_bf16 v[112:127], v[200:203], v[222:225], v[112:127]
	global_load_dwordx4 v[128:131], v176, s[28:29]
	ds_read_b128 v[208:211], v191
	v_mfma_f32_32x32x16_bf16 v[48:63], v[204:207], v[222:225], v[48:63]
	global_load_dwordx4 v[132:135], v177, s[28:29]
	ds_read_b128 v[212:215], v191 offset:2048
	s_waitcnt lgkmcnt(4)
	v_mfma_f32_32x32x16_bf16 v[96:111], v[200:203], v[226:229], v[96:111]
	global_load_dwordx4 v[136:139], v178, s[28:29]
	ds_read_b128 v[238:241], v251
	v_mfma_f32_32x32x16_bf16 v[32:47], v[204:207], v[226:229], v[32:47]
	ds_read_b128 v[242:245], v251 offset:2048
	s_waitcnt lgkmcnt(5)
	v_mfma_f32_32x32x16_bf16 v[80:95], v[200:203], v[230:233], v[80:95]
	global_load_dwordx4 v[140:143], v179, s[28:29]
	ds_read_b128 v[246:249], v251 offset:4096
	v_mfma_f32_32x32x16_bf16 v[16:31], v[204:207], v[230:233], v[16:31]
	global_load_dwordx4 v[144:147], v176, s[38:39]
	ds_read_b128 v[192:195], v251 offset:6144
	s_waitcnt lgkmcnt(6)
	v_mfma_f32_32x32x16_bf16 v[64:79], v[200:203], v[234:237], v[64:79]
	global_load_dwordx4 v[148:151], v177, s[38:39]
	v_mfma_f32_32x32x16_bf16 v[0:15], v[204:207], v[234:237], v[0:15]
	v_xad_u32 v190, v186, 64, s41
	v_xad_u32 v250, v188, 64, s41
	s_waitcnt lgkmcnt(3)
	v_mfma_f32_32x32x16_bf16 v[112:127], v[208:211], v[238:241], v[112:127]
	global_load_dwordx4 v[152:155], v178, s[38:39]
	ds_read_b128 v[200:203], v190
	v_mfma_f32_32x32x16_bf16 v[48:63], v[212:215], v[238:241], v[48:63]
	global_load_dwordx4 v[156:159], v179, s[38:39]
	ds_read_b128 v[204:207], v190 offset:2048
	s_waitcnt lgkmcnt(4)
	v_mfma_f32_32x32x16_bf16 v[96:111], v[208:211], v[242:245], v[96:111]
	global_load_dwordx4 v[160:163], v180, s[38:39]
	ds_read_b128 v[222:225], v250
	v_mfma_f32_32x32x16_bf16 v[32:47], v[212:215], v[242:245], v[32:47]
	ds_read_b128 v[226:229], v250 offset:2048
	s_waitcnt lgkmcnt(5)
	v_mfma_f32_32x32x16_bf16 v[80:95], v[208:211], v[246:249], v[80:95]
	global_load_dwordx4 v[164:167], v181, s[38:39]
	ds_read_b128 v[230:233], v250 offset:4096
	v_mfma_f32_32x32x16_bf16 v[16:31], v[212:215], v[246:249], v[16:31]
	global_load_dwordx4 v[168:171], v182, s[38:39]
	ds_read_b128 v[234:237], v250 offset:6144
	s_waitcnt lgkmcnt(6)
	v_mfma_f32_32x32x16_bf16 v[64:79], v[208:211], v[192:195], v[64:79]
	global_load_dwordx4 v[172:175], v184, s[38:39]
	v_mfma_f32_32x32x16_bf16 v[0:15], v[212:215], v[192:195], v[0:15]
	s_barrier
	v_xad_u32 v191, v187, 64, s41
	v_xad_u32 v251, v189, 64, s41
	s_waitcnt lgkmcnt(3)
	v_mfma_f32_32x32x16_bf16 v[112:127], v[200:203], v[222:225], v[112:127]
	ds_read_b128 v[208:211], v191
	v_mfma_f32_32x32x16_bf16 v[48:63], v[204:207], v[222:225], v[48:63]
	ds_read_b128 v[212:215], v191 offset:2048
	s_waitcnt lgkmcnt(4)
	v_mfma_f32_32x32x16_bf16 v[96:111], v[200:203], v[226:229], v[96:111]
	ds_read_b128 v[238:241], v251
	s_waitcnt vmcnt(11)
	ds_write_b128 v185, v[128:131]
	v_mfma_f32_32x32x16_bf16 v[32:47], v[204:207], v[226:229], v[32:47]
	ds_read_b128 v[242:245], v251 offset:2048
	s_waitcnt vmcnt(10)
	ds_write_b128 v185, v[132:135] offset:2048
	s_waitcnt lgkmcnt(7)
	v_mfma_f32_32x32x16_bf16 v[80:95], v[200:203], v[230:233], v[80:95]
	ds_read_b128 v[246:249], v251 offset:4096
	s_waitcnt vmcnt(9)
	ds_write_b128 v185, v[136:139] offset:4096
	v_mfma_f32_32x32x16_bf16 v[16:31], v[204:207], v[230:233], v[16:31]
	ds_read_b128 v[192:195], v251 offset:6144
	s_waitcnt vmcnt(8)
	ds_write_b128 v185, v[140:143] offset:6144
	s_waitcnt lgkmcnt(10)
	v_mfma_f32_32x32x16_bf16 v[64:79], v[200:203], v[234:237], v[64:79]
	s_waitcnt vmcnt(7)
	ds_write_b128 v185, v[144:147] offset:8192
	v_mfma_f32_32x32x16_bf16 v[0:15], v[204:207], v[234:237], v[0:15]
	s_waitcnt vmcnt(6)
	ds_write_b128 v185, v[148:151] offset:10240
	s_waitcnt lgkmcnt(9)
	v_mfma_f32_32x32x16_bf16 v[112:127], v[208:211], v[238:241], v[112:127]
	s_waitcnt vmcnt(5)
	ds_write_b128 v185, v[152:155] offset:12288
	v_mfma_f32_32x32x16_bf16 v[48:63], v[212:215], v[238:241], v[48:63]
	s_waitcnt vmcnt(4)
	ds_write_b128 v185, v[156:159] offset:14336
	s_waitcnt lgkmcnt(9)
	v_mfma_f32_32x32x16_bf16 v[96:111], v[208:211], v[242:245], v[96:111]
	s_waitcnt vmcnt(3)
	ds_write_b128 v185, v[160:163] offset:16384
	v_mfma_f32_32x32x16_bf16 v[32:47], v[212:215], v[242:245], v[32:47]
	s_waitcnt vmcnt(2)
	ds_write_b128 v185, v[164:167] offset:18432
	s_waitcnt lgkmcnt(9)
	v_mfma_f32_32x32x16_bf16 v[80:95], v[208:211], v[246:249], v[80:95]
	s_waitcnt vmcnt(1)
	ds_write_b128 v185, v[168:171] offset:20480
	v_mfma_f32_32x32x16_bf16 v[16:31], v[212:215], v[246:249], v[16:31]
	s_waitcnt vmcnt(0)
	ds_write_b128 v185, v[172:175] offset:22528
	s_waitcnt lgkmcnt(9)
	v_mfma_f32_32x32x16_bf16 v[64:79], v[208:211], v[192:195], v[64:79]
	v_mfma_f32_32x32x16_bf16 v[0:15], v[212:215], v[192:195], v[0:15]
	s_add_u32 s28, s28, 0x80
	s_addc_u32 s29, s29, 0
	s_add_u32 s38, s38, 0x80
	s_addc_u32 s39, s39, 0
	s_sub_i32 s40, s40, 0x6000
	s_cmp_lt_i32 s40, 0
	s_cselect_b32 s42, 0x12000, 0
	s_add_i32 s40, s40, s42
	s_sub_i32 s41, s41, 0x6000
	s_cmp_lt_i32 s41, 0
	s_cselect_b32 s42, 0x12000, 0
	s_add_i32 s41, s41, s42
	v_subrev_u32_e32 v196, 0x6000, v185
	v_add_u32_e32 v198, 0xc000, v185
	v_min_u32_e32 v185, v196, v198
	s_add_i32 s7, s7, 1
	s_cmp_lt_u32 s7, 15
	s_waitcnt lgkmcnt(0)
	s_barrier
	s_cbranch_scc1 .Lg4_loop
	v_add_u32_e32 v190, s40, v186
	v_add_u32_e32 v191, s40, v187
	v_add_u32_e32 v250, s40, v188
	v_add_u32_e32 v251, s40, v189
	ds_read_b128 v[200:203], v190
	ds_read_b128 v[204:207], v190 offset:2048
	ds_read_b128 v[222:225], v250
	ds_read_b128 v[226:229], v250 offset:2048
	ds_read_b128 v[230:233], v250 offset:4096
	ds_read_b128 v[234:237], v250 offset:6144
	s_waitcnt lgkmcnt(3)
	v_mfma_f32_32x32x16_bf16 v[112:127], v[200:203], v[222:225], v[112:127]
	ds_read_b128 v[208:211], v191
	v_mfma_f32_32x32x16_bf16 v[48:63], v[204:207], v[222:225], v[48:63]
	ds_read_b128 v[212:215], v191 offset:2048
	s_waitcnt lgkmcnt(4)
	v_mfma_f32_32x32x16_bf16 v[96:111], v[200:203], v[226:229], v[96:111]
	ds_read_b128 v[238:241], v251
	v_mfma_f32_32x32x16_bf16 v[32:47], v[204:207], v[226:229], v[32:47]
	ds_read_b128 v[242:245], v251 offset:2048
	s_waitcnt lgkmcnt(5)
	v_mfma_f32_32x32x16_bf16 v[80:95], v[200:203], v[230:233], v[80:95]
	ds_read_b128 v[246:249], v251 offset:4096
	v_mfma_f32_32x32x16_bf16 v[16:31], v[204:207], v[230:233], v[16:31]
	ds_read_b128 v[192:195], v251 offset:6144
	s_waitcnt lgkmcnt(6)
	v_mfma_f32_32x32x16_bf16 v[64:79], v[200:203], v[234:237], v[64:79]
	v_mfma_f32_32x32x16_bf16 v[0:15], v[204:207], v[234:237], v[0:15]
	v_xad_u32 v190, v186, 64, s41
	v_xad_u32 v250, v188, 64, s41
	s_waitcnt lgkmcnt(3)
	v_mfma_f32_32x32x16_bf16 v[112:127], v[208:211], v[238:241], v[112:127]
	ds_read_b128 v[200:203], v190
	v_mfma_f32_32x32x16_bf16 v[48:63], v[212:215], v[238:241], v[48:63]
	ds_read_b128 v[204:207], v190 offset:2048
	s_waitcnt lgkmcnt(4)
	v_mfma_f32_32x32x16_bf16 v[96:111], v[208:211], v[242:245], v[96:111]
	ds_read_b128 v[222:225], v250
	v_mfma_f32_32x32x16_bf16 v[32:47], v[212:215], v[242:245], v[32:47]
	ds_read_b128 v[226:229], v250 offset:2048
	s_waitcnt lgkmcnt(5)
	v_mfma_f32_32x32x16_bf16 v[80:95], v[208:211], v[246:249], v[80:95]
	ds_read_b128 v[230:233], v250 offset:4096
	v_mfma_f32_32x32x16_bf16 v[16:31], v[212:215], v[246:249], v[16:31]
	ds_read_b128 v[234:237], v250 offset:6144
	s_waitcnt lgkmcnt(6)
	v_mfma_f32_32x32x16_bf16 v[64:79], v[208:211], v[192:195], v[64:79]
	v_mfma_f32_32x32x16_bf16 v[0:15], v[212:215], v[192:195], v[0:15]
	v_xad_u32 v191, v187, 64, s41
	v_xad_u32 v251, v189, 64, s41
	s_waitcnt lgkmcnt(3)
	v_mfma_f32_32x32x16_bf16 v[112:127], v[200:203], v[222:225], v[112:127]
	ds_read_b128 v[208:211], v191
	v_mfma_f32_32x32x16_bf16 v[48:63], v[204:207], v[222:225], v[48:63]
	ds_read_b128 v[212:215], v191 offset:2048
	s_waitcnt lgkmcnt(4)
	v_mfma_f32_32x32x16_bf16 v[96:111], v[200:203], v[226:229], v[96:111]
	ds_read_b128 v[238:241], v251
	v_mfma_f32_32x32x16_bf16 v[32:47], v[204:207], v[226:229], v[32:47]
	ds_read_b128 v[242:245], v251 offset:2048
	s_waitcnt lgkmcnt(5)
	v_mfma_f32_32x32x16_bf16 v[80:95], v[200:203], v[230:233], v[80:95]
	ds_read_b128 v[246:249], v251 offset:4096
	v_mfma_f32_32x32x16_bf16 v[16:31], v[204:207], v[230:233], v[16:31]
	ds_read_b128 v[192:195], v251 offset:6144
	s_waitcnt lgkmcnt(6)
	v_mfma_f32_32x32x16_bf16 v[64:79], v[200:203], v[234:237], v[64:79]
	v_mfma_f32_32x32x16_bf16 v[0:15], v[204:207], v[234:237], v[0:15]
	s_waitcnt lgkmcnt(3)
	v_mfma_f32_32x32x16_bf16 v[112:127], v[208:211], v[238:241], v[112:127]
	v_mfma_f32_32x32x16_bf16 v[48:63], v[212:215], v[238:241], v[48:63]
	s_waitcnt lgkmcnt(2)
	v_mfma_f32_32x32x16_bf16 v[96:111], v[208:211], v[242:245], v[96:111]
	v_mfma_f32_32x32x16_bf16 v[32:47], v[212:215], v[242:245], v[32:47]
	s_waitcnt lgkmcnt(1)
	v_mfma_f32_32x32x16_bf16 v[80:95], v[208:211], v[246:249], v[80:95]
	v_mfma_f32_32x32x16_bf16 v[16:31], v[212:215], v[246:249], v[16:31]
	s_waitcnt lgkmcnt(0)
	v_mfma_f32_32x32x16_bf16 v[64:79], v[208:211], v[192:195], v[64:79]
	v_mfma_f32_32x32x16_bf16 v[0:15], v[212:215], v[192:195], v[0:15]
	s_setprio 0
	s_nop 7
	s_nop 7

.Lg5_noraise:
.Lg5_loop:
	v_add_u32_e32 v190, s36, v186
	v_add_u32_e32 v191, s36, v187
	v_add_u32_e32 v250, s36, v188
	v_add_u32_e32 v251, s36, v189
	ds_read_b128 v[200:203], v190
	ds_read_b128 v[204:207], v190 offset:2048
	ds_read_b128 v[222:225], v250
	ds_read_b128 v[226:229], v250 offset:2048
	ds_read_b128 v[230:233], v250 offset:4096
	ds_read_b128 v[234:237], v250 offset:6144
	s_waitcnt lgkmcnt(3)
	v_mfma_f32_32x32x16_bf16 v[112:127], v[200:203], v[222:225], v[112:127]
	global_load_dwordx4 v[128:131], v178, s[42:43]
	ds_read_b128 v[208:211], v191
	v_mfma_f32_32x32x16_bf16 v[48:63], v[204:207], v[222:225], v[48:63]
	global_load_dwordx4 v[132:135], v179, s[42:43]
	ds_read_b128 v[212:215], v191 offset:2048
	s_waitcnt lgkmcnt(4)
	v_mfma_f32_32x32x16_bf16 v[96:111], v[200:203], v[226:229], v[96:111]
	global_load_dwordx4 v[136:139], v180, s[42:43]
	ds_read_b128 v[238:241], v251
	v_mfma_f32_32x32x16_bf16 v[32:47], v[204:207], v[226:229], v[32:47]
	ds_read_b128 v[242:245], v251 offset:2048
	s_waitcnt lgkmcnt(5)
	v_mfma_f32_32x32x16_bf16 v[80:95], v[200:203], v[230:233], v[80:95]
	global_load_dwordx4 v[140:143], v181, s[42:43]
	ds_read_b128 v[246:249], v251 offset:4096
	v_mfma_f32_32x32x16_bf16 v[16:31], v[204:207], v[230:233], v[16:31]
	global_load_dwordx4 v[144:147], v178, s[44:45]
	ds_read_b128 v[192:195], v251 offset:6144
	s_waitcnt lgkmcnt(6)
	v_mfma_f32_32x32x16_bf16 v[64:79], v[200:203], v[234:237], v[64:79]
	global_load_dwordx4 v[148:151], v179, s[44:45]
	v_mfma_f32_32x32x16_bf16 v[0:15], v[204:207], v[234:237], v[0:15]
	v_xad_u32 v190, v186, 64, s37
	v_xad_u32 v250, v188, 64, s37
	s_waitcnt lgkmcnt(3)
	v_mfma_f32_32x32x16_bf16 v[112:127], v[208:211], v[238:241], v[112:127]
	global_load_dwordx4 v[152:155], v180, s[44:45]
	ds_read_b128 v[200:203], v190
	v_mfma_f32_32x32x16_bf16 v[48:63], v[212:215], v[238:241], v[48:63]
	global_load_dwordx4 v[156:159], v181, s[44:45]
	ds_read_b128 v[204:207], v190 offset:2048
	s_waitcnt lgkmcnt(4)
	v_mfma_f32_32x32x16_bf16 v[96:111], v[208:211], v[242:245], v[96:111]
	global_load_dwordx4 v[160:163], v182, s[44:45]
	ds_read_b128 v[222:225], v250
	v_mfma_f32_32x32x16_bf16 v[32:47], v[212:215], v[242:245], v[32:47]
	ds_read_b128 v[226:229], v250 offset:2048
	s_waitcnt lgkmcnt(5)
	v_mfma_f32_32x32x16_bf16 v[80:95], v[208:211], v[246:249], v[80:95]
	global_load_dwordx4 v[164:167], v183, s[44:45]
	ds_read_b128 v[230:233], v250 offset:4096
	v_mfma_f32_32x32x16_bf16 v[16:31], v[212:215], v[246:249], v[16:31]
	global_load_dwordx4 v[168:171], v184, s[44:45]
	ds_read_b128 v[234:237], v250 offset:6144
	s_waitcnt lgkmcnt(6)
	v_mfma_f32_32x32x16_bf16 v[64:79], v[208:211], v[192:195], v[64:79]
	global_load_dwordx4 v[172:175], v185, s[44:45]
	v_mfma_f32_32x32x16_bf16 v[0:15], v[212:215], v[192:195], v[0:15]
	s_barrier
	v_xad_u32 v191, v187, 64, s37
	v_xad_u32 v251, v189, 64, s37
	s_waitcnt lgkmcnt(3)
	v_mfma_f32_32x32x16_bf16 v[112:127], v[200:203], v[222:225], v[112:127]
	ds_read_b128 v[208:211], v191
	v_mfma_f32_32x32x16_bf16 v[48:63], v[204:207], v[222:225], v[48:63]
	ds_read_b128 v[212:215], v191 offset:2048
	s_waitcnt lgkmcnt(4)
	v_mfma_f32_32x32x16_bf16 v[96:111], v[200:203], v[226:229], v[96:111]
	ds_read_b128 v[238:241], v251
	s_waitcnt vmcnt(11)
	ds_write_b128 v177, v[128:131]
	v_mfma_f32_32x32x16_bf16 v[32:47], v[204:207], v[226:229], v[32:47]
	ds_read_b128 v[242:245], v251 offset:2048
	s_waitcnt vmcnt(10)
	ds_write_b128 v177, v[132:135] offset:2048
	s_waitcnt lgkmcnt(7)
	v_mfma_f32_32x32x16_bf16 v[80:95], v[200:203], v[230:233], v[80:95]
	ds_read_b128 v[246:249], v251 offset:4096
	s_waitcnt vmcnt(9)
	ds_write_b128 v177, v[136:139] offset:4096
	v_mfma_f32_32x32x16_bf16 v[16:31], v[204:207], v[230:233], v[16:31]
	ds_read_b128 v[192:195], v251 offset:6144
	s_waitcnt vmcnt(8)
	ds_write_b128 v177, v[140:143] offset:6144
	s_waitcnt lgkmcnt(10)
	v_mfma_f32_32x32x16_bf16 v[64:79], v[200:203], v[234:237], v[64:79]
	s_waitcnt vmcnt(7)
	ds_write_b128 v177, v[144:147] offset:8192
	v_mfma_f32_32x32x16_bf16 v[0:15], v[204:207], v[234:237], v[0:15]
	s_waitcnt vmcnt(6)
	ds_write_b128 v177, v[148:151] offset:10240
	s_waitcnt lgkmcnt(9)
	v_mfma_f32_32x32x16_bf16 v[112:127], v[208:211], v[238:241], v[112:127]
	s_waitcnt vmcnt(5)
	ds_write_b128 v177, v[152:155] offset:12288
	v_mfma_f32_32x32x16_bf16 v[48:63], v[212:215], v[238:241], v[48:63]
	s_waitcnt vmcnt(4)
	ds_write_b128 v177, v[156:159] offset:14336
	s_waitcnt lgkmcnt(9)
	v_mfma_f32_32x32x16_bf16 v[96:111], v[208:211], v[242:245], v[96:111]
	s_waitcnt vmcnt(3)
	ds_write_b128 v177, v[160:163] offset:16384
	v_mfma_f32_32x32x16_bf16 v[32:47], v[212:215], v[242:245], v[32:47]
	s_waitcnt vmcnt(2)
	ds_write_b128 v177, v[164:167] offset:18432
	s_waitcnt lgkmcnt(9)
	v_mfma_f32_32x32x16_bf16 v[80:95], v[208:211], v[246:249], v[80:95]
	s_waitcnt vmcnt(1)
	ds_write_b128 v177, v[168:171] offset:20480
	v_mfma_f32_32x32x16_bf16 v[16:31], v[212:215], v[246:249], v[16:31]
	s_waitcnt vmcnt(0)
	ds_write_b128 v177, v[172:175] offset:22528
	s_waitcnt lgkmcnt(9)
	v_mfma_f32_32x32x16_bf16 v[64:79], v[208:211], v[192:195], v[64:79]
	v_mfma_f32_32x32x16_bf16 v[0:15], v[212:215], v[192:195], v[0:15]
	s_add_u32 s42, s42, 0x80
	s_addc_u32 s43, s43, 0
	s_add_u32 s44, s44, 0x80
	s_addc_u32 s45, s45, 0
	s_sub_i32 s36, s36, 0x6000
	s_cmp_lt_i32 s36, 0
	s_cselect_b32 s38, 0x12000, 0
	s_add_i32 s36, s36, s38
	s_sub_i32 s37, s37, 0x6000
	s_cmp_lt_i32 s37, 0
	s_cselect_b32 s38, 0x12000, 0
	s_add_i32 s37, s37, s38
	v_subrev_u32_e32 v196, 0x6000, v177
	v_add_u32_e32 v198, 0xc000, v177
	v_min_u32_e32 v177, v196, v198
	s_add_i32 s1, s1, 1
	s_cmp_lt_u32 s1, 15
	s_waitcnt lgkmcnt(0)
	s_barrier
	s_cbranch_scc1 .Lg5_loop
	v_add_u32_e32 v190, s36, v186
	v_add_u32_e32 v191, s36, v187
	v_add_u32_e32 v250, s36, v188
	v_add_u32_e32 v251, s36, v189
	ds_read_b128 v[200:203], v190
	ds_read_b128 v[204:207], v190 offset:2048
	ds_read_b128 v[222:225], v250
	ds_read_b128 v[226:229], v250 offset:2048
	ds_read_b128 v[230:233], v250 offset:4096
	ds_read_b128 v[234:237], v250 offset:6144
	s_waitcnt lgkmcnt(3)
	v_mfma_f32_32x32x16_bf16 v[112:127], v[200:203], v[222:225], v[112:127]
	ds_read_b128 v[208:211], v191
	v_mfma_f32_32x32x16_bf16 v[48:63], v[204:207], v[222:225], v[48:63]
	ds_read_b128 v[212:215], v191 offset:2048
	s_waitcnt lgkmcnt(4)
	v_mfma_f32_32x32x16_bf16 v[96:111], v[200:203], v[226:229], v[96:111]
	ds_read_b128 v[238:241], v251
	v_mfma_f32_32x32x16_bf16 v[32:47], v[204:207], v[226:229], v[32:47]
	ds_read_b128 v[242:245], v251 offset:2048
	s_waitcnt lgkmcnt(5)
	v_mfma_f32_32x32x16_bf16 v[80:95], v[200:203], v[230:233], v[80:95]
	ds_read_b128 v[246:249], v251 offset:4096
	v_mfma_f32_32x32x16_bf16 v[16:31], v[204:207], v[230:233], v[16:31]
	ds_read_b128 v[192:195], v251 offset:6144
	s_waitcnt lgkmcnt(6)
	v_mfma_f32_32x32x16_bf16 v[64:79], v[200:203], v[234:237], v[64:79]
	v_mfma_f32_32x32x16_bf16 v[0:15], v[204:207], v[234:237], v[0:15]
	v_xad_u32 v190, v186, 64, s37
	v_xad_u32 v250, v188, 64, s37
	s_waitcnt lgkmcnt(3)
	v_mfma_f32_32x32x16_bf16 v[112:127], v[208:211], v[238:241], v[112:127]
	ds_read_b128 v[200:203], v190
	v_mfma_f32_32x32x16_bf16 v[48:63], v[212:215], v[238:241], v[48:63]
	ds_read_b128 v[204:207], v190 offset:2048
	s_waitcnt lgkmcnt(4)
	v_mfma_f32_32x32x16_bf16 v[96:111], v[208:211], v[242:245], v[96:111]
	ds_read_b128 v[222:225], v250
	v_mfma_f32_32x32x16_bf16 v[32:47], v[212:215], v[242:245], v[32:47]
	ds_read_b128 v[226:229], v250 offset:2048
	s_waitcnt lgkmcnt(5)
	v_mfma_f32_32x32x16_bf16 v[80:95], v[208:211], v[246:249], v[80:95]
	ds_read_b128 v[230:233], v250 offset:4096
	v_mfma_f32_32x32x16_bf16 v[16:31], v[212:215], v[246:249], v[16:31]
	ds_read_b128 v[234:237], v250 offset:6144
	s_waitcnt lgkmcnt(6)
	v_mfma_f32_32x32x16_bf16 v[64:79], v[208:211], v[192:195], v[64:79]
	v_mfma_f32_32x32x16_bf16 v[0:15], v[212:215], v[192:195], v[0:15]
	v_xad_u32 v191, v187, 64, s37
	v_xad_u32 v251, v189, 64, s37
	s_waitcnt lgkmcnt(3)
	v_mfma_f32_32x32x16_bf16 v[112:127], v[200:203], v[222:225], v[112:127]
	ds_read_b128 v[208:211], v191
	v_mfma_f32_32x32x16_bf16 v[48:63], v[204:207], v[222:225], v[48:63]
	ds_read_b128 v[212:215], v191 offset:2048
	s_waitcnt lgkmcnt(4)
	v_mfma_f32_32x32x16_bf16 v[96:111], v[200:203], v[226:229], v[96:111]
	ds_read_b128 v[238:241], v251
	v_mfma_f32_32x32x16_bf16 v[32:47], v[204:207], v[226:229], v[32:47]
	ds_read_b128 v[242:245], v251 offset:2048
	s_waitcnt lgkmcnt(5)
	v_mfma_f32_32x32x16_bf16 v[80:95], v[200:203], v[230:233], v[80:95]
	ds_read_b128 v[246:249], v251 offset:4096
	v_mfma_f32_32x32x16_bf16 v[16:31], v[204:207], v[230:233], v[16:31]
	ds_read_b128 v[192:195], v251 offset:6144
	s_waitcnt lgkmcnt(6)
	v_mfma_f32_32x32x16_bf16 v[64:79], v[200:203], v[234:237], v[64:79]
	v_mfma_f32_32x32x16_bf16 v[0:15], v[204:207], v[234:237], v[0:15]
	s_waitcnt lgkmcnt(3)
	v_mfma_f32_32x32x16_bf16 v[112:127], v[208:211], v[238:241], v[112:127]
	v_mfma_f32_32x32x16_bf16 v[48:63], v[212:215], v[238:241], v[48:63]
	s_waitcnt lgkmcnt(2)
	v_mfma_f32_32x32x16_bf16 v[96:111], v[208:211], v[242:245], v[96:111]
	v_mfma_f32_32x32x16_bf16 v[32:47], v[212:215], v[242:245], v[32:47]
	s_waitcnt lgkmcnt(1)
	v_mfma_f32_32x32x16_bf16 v[80:95], v[208:211], v[246:249], v[80:95]
	v_mfma_f32_32x32x16_bf16 v[16:31], v[212:215], v[246:249], v[16:31]
	s_waitcnt lgkmcnt(0)
	v_mfma_f32_32x32x16_bf16 v[64:79], v[208:211], v[192:195], v[64:79]
	v_mfma_f32_32x32x16_bf16 v[0:15], v[212:215], v[192:195], v[0:15]
	s_setprio 0
	s_nop 7
	s_nop 7
	s_branch .LBB0_482

.Lg6_noraise:
.Lg6_loop:
	v_add_u32_e32 v190, s40, v186
	v_add_u32_e32 v191, s40, v187
	v_add_u32_e32 v250, s40, v188
	v_add_u32_e32 v251, s40, v189
	ds_read_b128 v[200:203], v190
	ds_read_b128 v[204:207], v190 offset:2048
	ds_read_b128 v[222:225], v250
	ds_read_b128 v[226:229], v250 offset:2048
	ds_read_b128 v[230:233], v250 offset:4096
	ds_read_b128 v[234:237], v250 offset:6144
	s_waitcnt lgkmcnt(3)
	v_mfma_f32_32x32x16_bf16 v[112:127], v[200:203], v[222:225], v[112:127]
	global_load_dwordx4 v[128:131], v176, s[28:29]
	ds_read_b128 v[208:211], v191
	v_mfma_f32_32x32x16_bf16 v[48:63], v[204:207], v[222:225], v[48:63]
	global_load_dwordx4 v[132:135], v177, s[28:29]
	ds_read_b128 v[212:215], v191 offset:2048
	s_waitcnt lgkmcnt(4)
	v_mfma_f32_32x32x16_bf16 v[96:111], v[200:203], v[226:229], v[96:111]
	global_load_dwordx4 v[136:139], v178, s[28:29]
	ds_read_b128 v[238:241], v251
	v_mfma_f32_32x32x16_bf16 v[32:47], v[204:207], v[226:229], v[32:47]
	ds_read_b128 v[242:245], v251 offset:2048
	s_waitcnt lgkmcnt(5)
	v_mfma_f32_32x32x16_bf16 v[80:95], v[200:203], v[230:233], v[80:95]
	global_load_dwordx4 v[140:143], v179, s[28:29]
	ds_read_b128 v[246:249], v251 offset:4096
	v_mfma_f32_32x32x16_bf16 v[16:31], v[204:207], v[230:233], v[16:31]
	global_load_dwordx4 v[144:147], v176, s[38:39]
	ds_read_b128 v[192:195], v251 offset:6144
	s_waitcnt lgkmcnt(6)
	v_mfma_f32_32x32x16_bf16 v[64:79], v[200:203], v[234:237], v[64:79]
	global_load_dwordx4 v[148:151], v177, s[38:39]
	v_mfma_f32_32x32x16_bf16 v[0:15], v[204:207], v[234:237], v[0:15]
	v_xad_u32 v190, v186, 64, s41
	v_xad_u32 v250, v188, 64, s41
	s_waitcnt lgkmcnt(3)
	v_mfma_f32_32x32x16_bf16 v[112:127], v[208:211], v[238:241], v[112:127]
	global_load_dwordx4 v[152:155], v178, s[38:39]
	ds_read_b128 v[200:203], v190
	v_mfma_f32_32x32x16_bf16 v[48:63], v[212:215], v[238:241], v[48:63]
	global_load_dwordx4 v[156:159], v179, s[38:39]
	ds_read_b128 v[204:207], v190 offset:2048
	s_waitcnt lgkmcnt(4)
	v_mfma_f32_32x32x16_bf16 v[96:111], v[208:211], v[242:245], v[96:111]
	global_load_dwordx4 v[160:163], v180, s[38:39]
	ds_read_b128 v[222:225], v250
	v_mfma_f32_32x32x16_bf16 v[32:47], v[212:215], v[242:245], v[32:47]
	ds_read_b128 v[226:229], v250 offset:2048
	s_waitcnt lgkmcnt(5)
	v_mfma_f32_32x32x16_bf16 v[80:95], v[208:211], v[246:249], v[80:95]
	global_load_dwordx4 v[164:167], v181, s[38:39]
	ds_read_b128 v[230:233], v250 offset:4096
	v_mfma_f32_32x32x16_bf16 v[16:31], v[212:215], v[246:249], v[16:31]
	global_load_dwordx4 v[168:171], v182, s[38:39]
	ds_read_b128 v[234:237], v250 offset:6144
	s_waitcnt lgkmcnt(6)
	v_mfma_f32_32x32x16_bf16 v[64:79], v[208:211], v[192:195], v[64:79]
	global_load_dwordx4 v[172:175], v184, s[38:39]
	v_mfma_f32_32x32x16_bf16 v[0:15], v[212:215], v[192:195], v[0:15]
	s_barrier
	v_xad_u32 v191, v187, 64, s41
	v_xad_u32 v251, v189, 64, s41
	s_waitcnt lgkmcnt(3)
	v_mfma_f32_32x32x16_bf16 v[112:127], v[200:203], v[222:225], v[112:127]
	ds_read_b128 v[208:211], v191
	v_mfma_f32_32x32x16_bf16 v[48:63], v[204:207], v[222:225], v[48:63]
	ds_read_b128 v[212:215], v191 offset:2048
	s_waitcnt lgkmcnt(4)
	v_mfma_f32_32x32x16_bf16 v[96:111], v[200:203], v[226:229], v[96:111]
	ds_read_b128 v[238:241], v251
	s_waitcnt vmcnt(11)
	ds_write_b128 v185, v[128:131]
	v_mfma_f32_32x32x16_bf16 v[32:47], v[204:207], v[226:229], v[32:47]
	ds_read_b128 v[242:245], v251 offset:2048
	s_waitcnt vmcnt(10)
	ds_write_b128 v185, v[132:135] offset:2048
	s_waitcnt lgkmcnt(7)
	v_mfma_f32_32x32x16_bf16 v[80:95], v[200:203], v[230:233], v[80:95]
	ds_read_b128 v[246:249], v251 offset:4096
	s_waitcnt vmcnt(9)
	ds_write_b128 v185, v[136:139] offset:4096
	v_mfma_f32_32x32x16_bf16 v[16:31], v[204:207], v[230:233], v[16:31]
	ds_read_b128 v[192:195], v251 offset:6144
	s_waitcnt vmcnt(8)
	ds_write_b128 v185, v[140:143] offset:6144
	s_waitcnt lgkmcnt(10)
	v_mfma_f32_32x32x16_bf16 v[64:79], v[200:203], v[234:237], v[64:79]
	s_waitcnt vmcnt(7)
	ds_write_b128 v185, v[144:147] offset:8192
	v_mfma_f32_32x32x16_bf16 v[0:15], v[204:207], v[234:237], v[0:15]
	s_waitcnt vmcnt(6)
	ds_write_b128 v185, v[148:151] offset:10240
	s_waitcnt lgkmcnt(9)
	v_mfma_f32_32x32x16_bf16 v[112:127], v[208:211], v[238:241], v[112:127]
	s_waitcnt vmcnt(5)
	ds_write_b128 v185, v[152:155] offset:12288
	v_mfma_f32_32x32x16_bf16 v[48:63], v[212:215], v[238:241], v[48:63]
	s_waitcnt vmcnt(4)
	ds_write_b128 v185, v[156:159] offset:14336
	s_waitcnt lgkmcnt(9)
	v_mfma_f32_32x32x16_bf16 v[96:111], v[208:211], v[242:245], v[96:111]
	s_waitcnt vmcnt(3)
	ds_write_b128 v185, v[160:163] offset:16384
	v_mfma_f32_32x32x16_bf16 v[32:47], v[212:215], v[242:245], v[32:47]
	s_waitcnt vmcnt(2)
	ds_write_b128 v185, v[164:167] offset:18432
	s_waitcnt lgkmcnt(9)
	v_mfma_f32_32x32x16_bf16 v[80:95], v[208:211], v[246:249], v[80:95]
	s_waitcnt vmcnt(1)
	ds_write_b128 v185, v[168:171] offset:20480
	v_mfma_f32_32x32x16_bf16 v[16:31], v[212:215], v[246:249], v[16:31]
	s_waitcnt vmcnt(0)
	ds_write_b128 v185, v[172:175] offset:22528
	s_waitcnt lgkmcnt(9)
	v_mfma_f32_32x32x16_bf16 v[64:79], v[208:211], v[192:195], v[64:79]
	v_mfma_f32_32x32x16_bf16 v[0:15], v[212:215], v[192:195], v[0:15]
	s_add_u32 s28, s28, 0x80
	s_addc_u32 s29, s29, 0
	s_add_u32 s38, s38, 0x80
	s_addc_u32 s39, s39, 0
	s_sub_i32 s40, s40, 0x6000
	s_cmp_lt_i32 s40, 0
	s_cselect_b32 s42, 0x12000, 0
	s_add_i32 s40, s40, s42
	s_sub_i32 s41, s41, 0x6000
	s_cmp_lt_i32 s41, 0
	s_cselect_b32 s42, 0x12000, 0
	s_add_i32 s41, s41, s42
	v_subrev_u32_e32 v196, 0x6000, v185
	v_add_u32_e32 v198, 0xc000, v185
	v_min_u32_e32 v185, v196, v198
	s_add_i32 s7, s7, 1
	s_cmp_lt_u32 s7, 63
	s_waitcnt lgkmcnt(0)
	s_barrier
	s_cbranch_scc1 .Lg6_loop
	v_add_u32_e32 v190, s40, v186
	v_add_u32_e32 v191, s40, v187
	v_add_u32_e32 v250, s40, v188
	v_add_u32_e32 v251, s40, v189
	ds_read_b128 v[200:203], v190
	ds_read_b128 v[204:207], v190 offset:2048
	ds_read_b128 v[222:225], v250
	ds_read_b128 v[226:229], v250 offset:2048
	ds_read_b128 v[230:233], v250 offset:4096
	ds_read_b128 v[234:237], v250 offset:6144
	s_waitcnt lgkmcnt(3)
	v_mfma_f32_32x32x16_bf16 v[112:127], v[200:203], v[222:225], v[112:127]
	ds_read_b128 v[208:211], v191
	v_mfma_f32_32x32x16_bf16 v[48:63], v[204:207], v[222:225], v[48:63]
	ds_read_b128 v[212:215], v191 offset:2048
	s_waitcnt lgkmcnt(4)
	v_mfma_f32_32x32x16_bf16 v[96:111], v[200:203], v[226:229], v[96:111]
	ds_read_b128 v[238:241], v251
	v_mfma_f32_32x32x16_bf16 v[32:47], v[204:207], v[226:229], v[32:47]
	ds_read_b128 v[242:245], v251 offset:2048
	s_waitcnt lgkmcnt(5)
	v_mfma_f32_32x32x16_bf16 v[80:95], v[200:203], v[230:233], v[80:95]
	ds_read_b128 v[246:249], v251 offset:4096
	v_mfma_f32_32x32x16_bf16 v[16:31], v[204:207], v[230:233], v[16:31]
	ds_read_b128 v[192:195], v251 offset:6144
	s_waitcnt lgkmcnt(6)
	v_mfma_f32_32x32x16_bf16 v[64:79], v[200:203], v[234:237], v[64:79]
	v_mfma_f32_32x32x16_bf16 v[0:15], v[204:207], v[234:237], v[0:15]
	v_xad_u32 v190, v186, 64, s41
	v_xad_u32 v250, v188, 64, s41
	s_waitcnt lgkmcnt(3)
	v_mfma_f32_32x32x16_bf16 v[112:127], v[208:211], v[238:241], v[112:127]
	ds_read_b128 v[200:203], v190
	v_mfma_f32_32x32x16_bf16 v[48:63], v[212:215], v[238:241], v[48:63]
	ds_read_b128 v[204:207], v190 offset:2048
	s_waitcnt lgkmcnt(4)
	v_mfma_f32_32x32x16_bf16 v[96:111], v[208:211], v[242:245], v[96:111]
	ds_read_b128 v[222:225], v250
	v_mfma_f32_32x32x16_bf16 v[32:47], v[212:215], v[242:245], v[32:47]
	ds_read_b128 v[226:229], v250 offset:2048
	s_waitcnt lgkmcnt(5)
	v_mfma_f32_32x32x16_bf16 v[80:95], v[208:211], v[246:249], v[80:95]
	ds_read_b128 v[230:233], v250 offset:4096
	v_mfma_f32_32x32x16_bf16 v[16:31], v[212:215], v[246:249], v[16:31]
	ds_read_b128 v[234:237], v250 offset:6144
	s_waitcnt lgkmcnt(6)
	v_mfma_f32_32x32x16_bf16 v[64:79], v[208:211], v[192:195], v[64:79]
	v_mfma_f32_32x32x16_bf16 v[0:15], v[212:215], v[192:195], v[0:15]
	v_xad_u32 v191, v187, 64, s41
	v_xad_u32 v251, v189, 64, s41
	s_waitcnt lgkmcnt(3)
	v_mfma_f32_32x32x16_bf16 v[112:127], v[200:203], v[222:225], v[112:127]
	ds_read_b128 v[208:211], v191
	v_mfma_f32_32x32x16_bf16 v[48:63], v[204:207], v[222:225], v[48:63]
	ds_read_b128 v[212:215], v191 offset:2048
	s_waitcnt lgkmcnt(4)
	v_mfma_f32_32x32x16_bf16 v[96:111], v[200:203], v[226:229], v[96:111]
	ds_read_b128 v[238:241], v251
	v_mfma_f32_32x32x16_bf16 v[32:47], v[204:207], v[226:229], v[32:47]
	ds_read_b128 v[242:245], v251 offset:2048
	s_waitcnt lgkmcnt(5)
	v_mfma_f32_32x32x16_bf16 v[80:95], v[200:203], v[230:233], v[80:95]
	ds_read_b128 v[246:249], v251 offset:4096
	v_mfma_f32_32x32x16_bf16 v[16:31], v[204:207], v[230:233], v[16:31]
	ds_read_b128 v[192:195], v251 offset:6144
	s_waitcnt lgkmcnt(6)
	v_mfma_f32_32x32x16_bf16 v[64:79], v[200:203], v[234:237], v[64:79]
	v_mfma_f32_32x32x16_bf16 v[0:15], v[204:207], v[234:237], v[0:15]
	s_waitcnt lgkmcnt(3)
	v_mfma_f32_32x32x16_bf16 v[112:127], v[208:211], v[238:241], v[112:127]
	v_mfma_f32_32x32x16_bf16 v[48:63], v[212:215], v[238:241], v[48:63]
	s_waitcnt lgkmcnt(2)
	v_mfma_f32_32x32x16_bf16 v[96:111], v[208:211], v[242:245], v[96:111]
	v_mfma_f32_32x32x16_bf16 v[32:47], v[212:215], v[242:245], v[32:47]
	s_waitcnt lgkmcnt(1)
	v_mfma_f32_32x32x16_bf16 v[80:95], v[208:211], v[246:249], v[80:95]
	v_mfma_f32_32x32x16_bf16 v[16:31], v[212:215], v[246:249], v[16:31]
	s_waitcnt lgkmcnt(0)
	v_mfma_f32_32x32x16_bf16 v[64:79], v[208:211], v[192:195], v[64:79]
	v_mfma_f32_32x32x16_bf16 v[0:15], v[212:215], v[192:195], v[0:15]
	s_setprio 0
	s_nop 7
	s_nop 7
